# scan compute loop: last ring operand of the post-barrier read burst (ka of step 2) prefetched before the barrier; plus wait-as-padding and barrier at loop head
# baseline (speedup 1.0000x reference)
.LBB0_1047:
	s_and_b64 vcc, exec, s[24:25]
	s_cbranch_vccz .LBB0_1279
	s_waitcnt vmcnt(0)
	v_mov_b32_e32 v4, v232
	s_nop 0
	v_ashrrev_i32_e32 v0, 6, v4
	v_and_b32_e32 v54, 15, v4
	v_cmp_gt_i32_e32 vcc, 4, v0
	v_lshlrev_b32_e32 v38, 2, v54
	s_barrier
	s_and_saveexec_b64 s[24:25], vcc
	s_xor_b64 s[24:25], exec, s[24:25]
	s_cbranch_execz .LBB0_1051
	v_lshlrev_b32_e32 v2, 2, v4
	s_waitcnt lgkmcnt(0)
	s_barrier
	v_and_b32_e32 v2, 0xc0, v2
	v_lshl_or_b32 v85, v0, 8, v2
	v_mov_b32_e32 v74, 0
	v_lshlrev_b32_e32 v83, 4, v54
	v_add3_u32 v87, 0, v85, v38
	s_mov_b32 s26, 0
	s_mov_b32 s96, 0x12800
	v_mov_b32_e32 v75, v74
	v_mov_b32_e32 v76, v74
	v_mov_b32_e32 v77, v74
	v_add_u32_e32 v88, 0x12800, v83
	ds_read_b128 v[108:111], v88 offset:4096
	ds_read_b128 v[100:103], v88
	ds_read_b128 v[120:123], v88 offset:8192
	ds_read_b128 v[112:115], v88 offset:4352
	ds_read_b128 v[104:107], v88 offset:256
	ds_read_b128 v[128:131], v88 offset:8448
	ds_read_b128 v[124:127], v88 offset:4608
	ds_read_b128 v[116:119], v88 offset:512
	ds_read_b128 v[132:135], v88 offset:8704
	s_waitcnt lgkmcnt(0)
	s_and_b32 s2, s26, 1
	s_mul_i32 s3, s2, 0x5400
	v_lshlrev_b32_e32 v91, 2, v87
	v_lshl_add_u32 v91, s2, 14, v91
	s_add_i32 s2, s3, 0
	v_add_u32_e32 v0, s2, v85
	v_add_u32_e32 v89, s2, v83
	v_add_u32_e32 v90, s96, v83
	s_add_i32 s96, s96, 0x3000
	s_cmp_eq_u32 s96, 0x1e800
	s_cselect_b32 s96, 0x20200, s96
	s_cmp_eq_u32 s96, 0x23200
	s_cselect_b32 s96, 0x12800, s96
	v_add_u32_e32 v88, s96, v83
	s_setprio 3
	s_branch .Lscan_compute_entry

.Lscan_compute_entry:
	ds_read_b128 v[14:17], v0 offset:20480
	ds_read_b128 v[10:13], v0 offset:20496
	ds_read_b128 v[6:9], v0 offset:20512
	ds_read_b128 v[2:5], v0 offset:20528
	ds_read_b128 v[54:57], v89 offset:16384
	ds_read_b128 v[26:29], v89 offset:16640
	ds_read_b128 v[78:81], v89 offset:4096
	ds_read_b128 v[58:61], v89 offset:4352
	ds_read_b128 v[30:33], v89 offset:4608
	ds_read_b128 v[18:21], v89 offset:16896
	v_pk_mul_f32 v[66:67], v[74:75], v[108:109]
	s_waitcnt lgkmcnt(3)
	v_pk_mul_f32 v[78:79], v[14:15], v[78:79] op_sel_hi:[0,1]
	v_pk_fma_f32 v[66:67], v[76:77], v[110:111], v[66:67]
	v_pk_mul_f32 v[80:81], v[14:15], v[80:81] op_sel_hi:[0,1]
	v_add_f32_e32 v66, v66, v67
	v_pk_fma_f32 v[62:63], v[74:75], v[100:101], v[78:79]
	v_pk_fma_f32 v[64:65], v[76:77], v[102:103], v[80:81]
	v_add_f32_dpp v66, v66, v66 quad_perm:[1,0,3,2] row_mask:0xf bank_mask:0xf bound_ctrl:1
	v_mov_b32_e32 v0, v17
	v_mov_b32_e32 v82, v13
	v_add_f32_dpp v66, v66, v66 quad_perm:[2,3,0,1] row_mask:0xf bank_mask:0xf bound_ctrl:1
	v_mov_b32_e32 v84, v9
	v_mov_b32_e32 v86, v5
	v_add_f32_dpp v66, v66, v66 row_half_mirror row_mask:0xf bank_mask:0xf bound_ctrl:1
	s_add_i32 s26, s26, 1
	s_nop 0
	v_add_f32_dpp v66, v66, v66 row_ror:8 row_mask:0xf bank_mask:0xf bound_ctrl:1
	v_pk_fma_f32 v[62:63], v[120:121], v[66:67], v[62:63] op_sel_hi:[1,0,1] neg_lo:[1,0,0] neg_hi:[1,0,0]
	v_pk_fma_f32 v[64:65], v[122:123], v[66:67], v[64:65] op_sel_hi:[1,0,1] neg_lo:[1,0,0] neg_hi:[1,0,0]
	v_pk_mul_f32 v[50:51], v[112:113], v[62:63]
	v_pk_mul_f32 v[46:47], v[104:105], v[62:63]
	v_pk_fma_f32 v[50:51], v[114:115], v[64:65], v[50:51]
	s_waitcnt lgkmcnt(2)
	v_pk_fma_f32 v[66:67], v[14:15], v[58:59], v[46:47] op_sel:[1,0,0]
	v_add_f32_e32 v47, v50, v51
	v_pk_mul_f32 v[48:49], v[106:107], v[64:65]
	v_pk_mul_f32 v[56:57], v[56:57], v[64:65]
	v_add_f32_dpp v68, v47, v47 quad_perm:[1,0,3,2] row_mask:0xf bank_mask:0xf bound_ctrl:1
	v_pk_fma_f32 v[14:15], v[14:15], v[60:61], v[48:49] op_sel:[1,0,0]
	v_pk_fma_f32 v[54:55], v[54:55], v[62:63], v[56:57]
	v_add_f32_dpp v68, v68, v68 quad_perm:[2,3,0,1] row_mask:0xf bank_mask:0xf bound_ctrl:1
	v_add_f32_e32 v92, v54, v55
	s_nop 0
	v_add_f32_dpp v68, v68, v68 row_half_mirror row_mask:0xf bank_mask:0xf bound_ctrl:1
	ds_read_b128 v[46:49], v90 offset:768
	ds_read_b128 v[50:53], v89 offset:4864
	ds_read_b128 v[54:57], v90 offset:4864
	ds_read_b128 v[58:61], v90 offset:8960
	ds_read_b128 v[62:65], v89 offset:17152
	v_add_f32_dpp v68, v68, v68 row_ror:8 row_mask:0xf bank_mask:0xf bound_ctrl:1
	v_pk_fma_f32 v[42:43], v[128:129], v[68:69], v[66:67] op_sel_hi:[1,0,1] neg_lo:[1,0,0] neg_hi:[1,0,0]
	v_pk_fma_f32 v[14:15], v[130:131], v[68:69], v[14:15] op_sel_hi:[1,0,1] neg_lo:[1,0,0] neg_hi:[1,0,0]
	v_pk_mul_f32 v[38:39], v[124:125], v[42:43]
	v_pk_mul_f32 v[28:29], v[28:29], v[14:15]
	v_pk_mul_f32 v[36:37], v[118:119], v[14:15]
	v_pk_fma_f32 v[14:15], v[126:127], v[14:15], v[38:39]
	v_pk_mul_f32 v[34:35], v[116:117], v[42:43]
	v_add_f32_e32 v14, v14, v15
	v_pk_fma_f32 v[26:27], v[26:27], v[42:43], v[28:29]
	s_waitcnt lgkmcnt(6)
	v_pk_fma_f32 v[42:43], v[16:17], v[30:31], v[34:35] op_sel_hi:[0,1,1]
	v_add_f32_dpp v66, v14, v14 quad_perm:[1,0,3,2] row_mask:0xf bank_mask:0xf bound_ctrl:1
	v_pk_fma_f32 v[44:45], v[16:17], v[32:33], v[36:37] op_sel_hi:[0,1,1]
	v_add_f32_e32 v93, v26, v27
	v_add_f32_dpp v66, v66, v66 quad_perm:[2,3,0,1] row_mask:0xf bank_mask:0xf bound_ctrl:1
	ds_read_b128 v[14:17], v90 offset:1024
	ds_read_b128 v[26:29], v89 offset:5120
	ds_read_b128 v[30:33], v90 offset:5120
	ds_read_b128 v[34:37], v90 offset:9216
	ds_read_b128 v[38:41], v89 offset:17408
	v_add_f32_dpp v66, v66, v66 row_half_mirror row_mask:0xf bank_mask:0xf bound_ctrl:1
	s_nop 1
	v_add_f32_dpp v66, v66, v66 row_ror:8 row_mask:0xf bank_mask:0xf bound_ctrl:1
	v_pk_fma_f32 v[22:23], v[132:133], v[66:67], v[42:43] op_sel_hi:[1,0,1] neg_lo:[1,0,0] neg_hi:[1,0,0]
	v_pk_fma_f32 v[24:25], v[134:135], v[66:67], v[44:45] op_sel_hi:[1,0,1] neg_lo:[1,0,0] neg_hi:[1,0,0]
	s_waitcnt lgkmcnt(7)
	v_pk_mul_f32 v[42:43], v[54:55], v[22:23]
	v_pk_mul_f32 v[20:21], v[20:21], v[24:25]
	v_pk_mul_f32 v[44:45], v[46:47], v[22:23]
	v_pk_mul_f32 v[46:47], v[48:49], v[24:25]
	v_pk_fma_f32 v[18:19], v[18:19], v[22:23], v[20:21]
	v_pk_fma_f32 v[20:21], v[56:57], v[24:25], v[42:43]
	v_pk_fma_f32 v[54:55], v[0:1], v[50:51], v[44:45] op_sel_hi:[0,1,1]
	v_pk_fma_f32 v[56:57], v[0:1], v[52:53], v[46:47] op_sel_hi:[0,1,1]
	v_add_f32_e32 v94, v18, v19
	v_add_f32_e32 v18, v20, v21
	s_nop 0
	s_nop 0
	v_add_f32_dpp v0, v18, v18 quad_perm:[1,0,3,2] row_mask:0xf bank_mask:0xf bound_ctrl:1
	ds_read_b128 v[18:21], v90 offset:1280
	ds_read_b128 v[22:25], v89 offset:5376
	v_add_f32_dpp v0, v0, v0 quad_perm:[2,3,0,1] row_mask:0xf bank_mask:0xf bound_ctrl:1
	ds_read_b128 v[42:45], v90 offset:5376
	ds_read_b128 v[46:49], v90 offset:9472
	v_add_f32_dpp v0, v0, v0 row_half_mirror row_mask:0xf bank_mask:0xf bound_ctrl:1
	ds_read_b128 v[50:53], v89 offset:17664
	s_waitcnt lgkmcnt(11)
	v_add_f32_dpp v0, v0, v0 row_ror:8 row_mask:0xf bank_mask:0xf bound_ctrl:1
	v_pk_fma_f32 v[54:55], v[58:59], v[0:1], v[54:55] op_sel_hi:[1,0,1] neg_lo:[1,0,0] neg_hi:[1,0,0]
	v_pk_fma_f32 v[56:57], v[60:61], v[0:1], v[56:57] op_sel_hi:[1,0,1] neg_lo:[1,0,0] neg_hi:[1,0,0]
	s_waitcnt lgkmcnt(7)
	v_pk_mul_f32 v[30:31], v[30:31], v[54:55]
	v_pk_mul_f32 v[58:59], v[64:65], v[56:57]
	v_pk_mul_f32 v[14:15], v[14:15], v[54:55]
	v_pk_fma_f32 v[54:55], v[62:63], v[54:55], v[58:59]
	v_pk_fma_f32 v[30:31], v[32:33], v[56:57], v[30:31]
	v_pk_fma_f32 v[62:63], v[10:11], v[26:27], v[14:15] op_sel_hi:[0,1,1]
	v_add_f32_e32 v95, v54, v55
	v_add_f32_e32 v14, v30, v31
	ds_write_b128 v91, v[92:95] offset:43008
	v_pk_mul_f32 v[16:17], v[16:17], v[56:57]
	v_add_f32_dpp v0, v14, v14 quad_perm:[1,0,3,2] row_mask:0xf bank_mask:0xf bound_ctrl:1
	v_pk_fma_f32 v[64:65], v[10:11], v[28:29], v[16:17] op_sel_hi:[0,1,1]
	ds_read_b128 v[14:17], v90 offset:1536
	v_add_f32_dpp v0, v0, v0 quad_perm:[2,3,0,1] row_mask:0xf bank_mask:0xf bound_ctrl:1
	ds_read_b128 v[26:29], v89 offset:5632
	ds_read_b128 v[30:33], v90 offset:5632
	v_add_f32_dpp v0, v0, v0 row_half_mirror row_mask:0xf bank_mask:0xf bound_ctrl:1
	ds_read_b128 v[54:57], v90 offset:9728
	ds_read_b128 v[58:61], v89 offset:17920
	v_add_f32_dpp v0, v0, v0 row_ror:8 row_mask:0xf bank_mask:0xf bound_ctrl:1
	s_waitcnt lgkmcnt(12)
	v_pk_fma_f32 v[34:35], v[34:35], v[0:1], v[62:63] op_sel_hi:[1,0,1] neg_lo:[1,0,0] neg_hi:[1,0,0]
	v_pk_fma_f32 v[36:37], v[36:37], v[0:1], v[64:65] op_sel_hi:[1,0,1] neg_lo:[1,0,0] neg_hi:[1,0,0]
	s_waitcnt lgkmcnt(8)
	v_pk_mul_f32 v[42:43], v[42:43], v[34:35]
	v_pk_mul_f32 v[40:41], v[40:41], v[36:37]
	v_pk_mul_f32 v[18:19], v[18:19], v[34:35]
	v_pk_mul_f32 v[20:21], v[20:21], v[36:37]
	v_pk_fma_f32 v[34:35], v[38:39], v[34:35], v[40:41]
	v_pk_fma_f32 v[36:37], v[44:45], v[36:37], v[42:43]
	v_pk_fma_f32 v[62:63], v[10:11], v[22:23], v[18:19] op_sel:[1,0,0]
	v_add_f32_e32 v18, v36, v37
	v_add_f32_e32 v96, v34, v35
	v_pk_fma_f32 v[10:11], v[10:11], v[24:25], v[20:21] op_sel:[1,0,0]
	v_add_f32_dpp v0, v18, v18 quad_perm:[1,0,3,2] row_mask:0xf bank_mask:0xf bound_ctrl:1
	ds_read_b128 v[18:21], v90 offset:1792
	ds_read_b128 v[22:25], v89 offset:5888
	v_add_f32_dpp v0, v0, v0 quad_perm:[2,3,0,1] row_mask:0xf bank_mask:0xf bound_ctrl:1
	ds_read_b128 v[34:37], v90 offset:5888
	ds_read_b128 v[38:41], v90 offset:9984
	v_add_f32_dpp v0, v0, v0 row_half_mirror row_mask:0xf bank_mask:0xf bound_ctrl:1
	ds_read_b128 v[42:45], v89 offset:18176
	s_waitcnt lgkmcnt(12)
	v_add_f32_dpp v0, v0, v0 row_ror:8 row_mask:0xf bank_mask:0xf bound_ctrl:1
	v_pk_fma_f32 v[46:47], v[46:47], v[0:1], v[62:63] op_sel_hi:[1,0,1] neg_lo:[1,0,0] neg_hi:[1,0,0]
	v_pk_fma_f32 v[10:11], v[48:49], v[0:1], v[10:11] op_sel_hi:[1,0,1] neg_lo:[1,0,0] neg_hi:[1,0,0]
	s_waitcnt lgkmcnt(7)
	v_pk_mul_f32 v[30:31], v[30:31], v[46:47]
	v_pk_mul_f32 v[48:49], v[52:53], v[10:11]
	v_pk_mul_f32 v[14:15], v[14:15], v[46:47]
	v_pk_mul_f32 v[16:17], v[16:17], v[10:11]
	v_pk_fma_f32 v[46:47], v[50:51], v[46:47], v[48:49]
	v_pk_fma_f32 v[10:11], v[32:33], v[10:11], v[30:31]
	v_add_f32_e32 v10, v10, v11
	v_add_f32_e32 v97, v46, v47
	v_pk_fma_f32 v[50:51], v[12:13], v[26:27], v[14:15] op_sel_hi:[0,1,1]
	v_add_f32_dpp v0, v10, v10 quad_perm:[1,0,3,2] row_mask:0xf bank_mask:0xf bound_ctrl:1
	v_pk_fma_f32 v[52:53], v[12:13], v[28:29], v[16:17] op_sel_hi:[0,1,1]
	ds_read_b128 v[10:13], v90 offset:2048
	v_add_f32_dpp v0, v0, v0 quad_perm:[2,3,0,1] row_mask:0xf bank_mask:0xf bound_ctrl:1
	ds_read_b128 v[14:17], v89 offset:6144
	ds_read_b128 v[26:29], v90 offset:6144
	v_add_f32_dpp v0, v0, v0 row_half_mirror row_mask:0xf bank_mask:0xf bound_ctrl:1
	ds_read_b128 v[30:33], v90 offset:10240
	ds_read_b128 v[46:49], v89 offset:18432
	v_add_f32_dpp v0, v0, v0 row_ror:8 row_mask:0xf bank_mask:0xf bound_ctrl:1
	s_waitcnt lgkmcnt(11)
	v_pk_fma_f32 v[50:51], v[54:55], v[0:1], v[50:51] op_sel_hi:[1,0,1] neg_lo:[1,0,0] neg_hi:[1,0,0]
	v_pk_fma_f32 v[52:53], v[56:57], v[0:1], v[52:53] op_sel_hi:[1,0,1] neg_lo:[1,0,0] neg_hi:[1,0,0]
	s_waitcnt lgkmcnt(7)
	v_pk_mul_f32 v[34:35], v[34:35], v[50:51]
	v_pk_mul_f32 v[54:55], v[60:61], v[52:53]
	v_pk_mul_f32 v[18:19], v[18:19], v[50:51]
	v_pk_fma_f32 v[50:51], v[58:59], v[50:51], v[54:55]
	v_pk_fma_f32 v[34:35], v[36:37], v[52:53], v[34:35]
	v_pk_fma_f32 v[58:59], v[82:83], v[22:23], v[18:19] op_sel_hi:[0,1,1]
	v_add_f32_e32 v18, v34, v35
	v_add_f32_e32 v98, v50, v51
	v_pk_mul_f32 v[20:21], v[20:21], v[52:53]
	v_add_f32_dpp v0, v18, v18 quad_perm:[1,0,3,2] row_mask:0xf bank_mask:0xf bound_ctrl:1
	v_pk_fma_f32 v[60:61], v[82:83], v[24:25], v[20:21] op_sel_hi:[0,1,1]
	ds_read_b128 v[18:21], v90 offset:2304
	v_add_f32_dpp v0, v0, v0 quad_perm:[2,3,0,1] row_mask:0xf bank_mask:0xf bound_ctrl:1
	ds_read_b128 v[22:25], v89 offset:6400
	ds_read_b128 v[34:37], v90 offset:6400
	v_add_f32_dpp v0, v0, v0 row_half_mirror row_mask:0xf bank_mask:0xf bound_ctrl:1
	ds_read_b128 v[50:53], v90 offset:10496
	ds_read_b128 v[54:57], v89 offset:18688
	v_add_f32_dpp v0, v0, v0 row_ror:8 row_mask:0xf bank_mask:0xf bound_ctrl:1
	s_waitcnt lgkmcnt(11)
	v_pk_fma_f32 v[38:39], v[38:39], v[0:1], v[58:59] op_sel_hi:[1,0,1] neg_lo:[1,0,0] neg_hi:[1,0,0]
	v_pk_fma_f32 v[40:41], v[40:41], v[0:1], v[60:61] op_sel_hi:[1,0,1] neg_lo:[1,0,0] neg_hi:[1,0,0]
	s_waitcnt lgkmcnt(7)
	v_pk_mul_f32 v[26:27], v[26:27], v[38:39]
	v_pk_mul_f32 v[44:45], v[44:45], v[40:41]
	v_pk_mul_f32 v[10:11], v[10:11], v[38:39]
	v_pk_fma_f32 v[38:39], v[42:43], v[38:39], v[44:45]
	v_pk_fma_f32 v[26:27], v[28:29], v[40:41], v[26:27]
	v_pk_fma_f32 v[58:59], v[6:7], v[14:15], v[10:11] op_sel_hi:[0,1,1]
	v_add_f32_e32 v99, v38, v39
	v_add_f32_e32 v10, v26, v27
	ds_write_b128 v91, v[96:99] offset:47104
	v_pk_mul_f32 v[12:13], v[12:13], v[40:41]
	v_add_f32_dpp v0, v10, v10 quad_perm:[1,0,3,2] row_mask:0xf bank_mask:0xf bound_ctrl:1
	v_pk_fma_f32 v[60:61], v[6:7], v[16:17], v[12:13] op_sel_hi:[0,1,1]
	ds_read_b128 v[10:13], v90 offset:2560
	v_add_f32_dpp v0, v0, v0 quad_perm:[2,3,0,1] row_mask:0xf bank_mask:0xf bound_ctrl:1
	ds_read_b128 v[14:17], v89 offset:6656
	ds_read_b128 v[26:29], v90 offset:6656
	v_add_f32_dpp v0, v0, v0 row_half_mirror row_mask:0xf bank_mask:0xf bound_ctrl:1
	ds_read_b128 v[38:41], v90 offset:10752
	ds_read_b128 v[42:45], v89 offset:18944
	v_add_f32_dpp v0, v0, v0 row_ror:8 row_mask:0xf bank_mask:0xf bound_ctrl:1
	s_waitcnt lgkmcnt(12)
	v_pk_fma_f32 v[30:31], v[30:31], v[0:1], v[58:59] op_sel_hi:[1,0,1] neg_lo:[1,0,0] neg_hi:[1,0,0]
	v_pk_fma_f32 v[32:33], v[32:33], v[0:1], v[60:61] op_sel_hi:[1,0,1] neg_lo:[1,0,0] neg_hi:[1,0,0]
	s_waitcnt lgkmcnt(8)
	v_pk_mul_f32 v[34:35], v[34:35], v[30:31]
	v_pk_mul_f32 v[48:49], v[48:49], v[32:33]
	v_pk_mul_f32 v[18:19], v[18:19], v[30:31]
	v_pk_mul_f32 v[20:21], v[20:21], v[32:33]
	v_pk_fma_f32 v[30:31], v[46:47], v[30:31], v[48:49]
	v_pk_fma_f32 v[32:33], v[36:37], v[32:33], v[34:35]
	v_pk_fma_f32 v[58:59], v[6:7], v[22:23], v[18:19] op_sel:[1,0,0]
	v_add_f32_e32 v18, v32, v33
	v_add_f32_e32 v92, v30, v31
	v_pk_fma_f32 v[6:7], v[6:7], v[24:25], v[20:21] op_sel:[1,0,0]
	v_add_f32_dpp v0, v18, v18 quad_perm:[1,0,3,2] row_mask:0xf bank_mask:0xf bound_ctrl:1
	ds_read_b128 v[18:21], v90 offset:2816
	ds_read_b128 v[22:25], v89 offset:6912
	v_add_f32_dpp v0, v0, v0 quad_perm:[2,3,0,1] row_mask:0xf bank_mask:0xf bound_ctrl:1
	ds_read_b128 v[30:33], v90 offset:6912
	ds_read_b128 v[34:37], v90 offset:11008
	v_add_f32_dpp v0, v0, v0 row_half_mirror row_mask:0xf bank_mask:0xf bound_ctrl:1
	ds_read_b128 v[46:49], v89 offset:19200
	s_waitcnt lgkmcnt(12)
	v_add_f32_dpp v0, v0, v0 row_ror:8 row_mask:0xf bank_mask:0xf bound_ctrl:1
	v_pk_fma_f32 v[50:51], v[50:51], v[0:1], v[58:59] op_sel_hi:[1,0,1] neg_lo:[1,0,0] neg_hi:[1,0,0]
	v_pk_fma_f32 v[6:7], v[52:53], v[0:1], v[6:7] op_sel_hi:[1,0,1] neg_lo:[1,0,0] neg_hi:[1,0,0]
	s_waitcnt lgkmcnt(7)
	v_pk_mul_f32 v[26:27], v[26:27], v[50:51]
	v_pk_mul_f32 v[52:53], v[56:57], v[6:7]
	v_pk_mul_f32 v[10:11], v[10:11], v[50:51]
	v_pk_mul_f32 v[12:13], v[12:13], v[6:7]
	v_pk_fma_f32 v[50:51], v[54:55], v[50:51], v[52:53]
	v_pk_fma_f32 v[6:7], v[28:29], v[6:7], v[26:27]
	v_add_f32_e32 v6, v6, v7
	v_add_f32_e32 v93, v50, v51
	v_pk_fma_f32 v[54:55], v[8:9], v[14:15], v[10:11] op_sel_hi:[0,1,1]
	v_add_f32_dpp v0, v6, v6 quad_perm:[1,0,3,2] row_mask:0xf bank_mask:0xf bound_ctrl:1
	v_pk_fma_f32 v[56:57], v[8:9], v[16:17], v[12:13] op_sel_hi:[0,1,1]
	ds_read_b128 v[6:9], v90 offset:3072
	v_add_f32_dpp v0, v0, v0 quad_perm:[2,3,0,1] row_mask:0xf bank_mask:0xf bound_ctrl:1
	ds_read_b128 v[10:13], v89 offset:7168
	ds_read_b128 v[14:17], v90 offset:7168
	v_add_f32_dpp v0, v0, v0 row_half_mirror row_mask:0xf bank_mask:0xf bound_ctrl:1
	ds_read_b128 v[26:29], v90 offset:11264
	ds_read_b128 v[50:53], v89 offset:19456
	v_add_f32_dpp v0, v0, v0 row_ror:8 row_mask:0xf bank_mask:0xf bound_ctrl:1
	s_waitcnt lgkmcnt(11)
	v_pk_fma_f32 v[38:39], v[38:39], v[0:1], v[54:55] op_sel_hi:[1,0,1] neg_lo:[1,0,0] neg_hi:[1,0,0]
	v_pk_fma_f32 v[40:41], v[40:41], v[0:1], v[56:57] op_sel_hi:[1,0,1] neg_lo:[1,0,0] neg_hi:[1,0,0]
	s_waitcnt lgkmcnt(7)
	v_pk_mul_f32 v[30:31], v[30:31], v[38:39]
	v_pk_mul_f32 v[44:45], v[44:45], v[40:41]
	v_pk_mul_f32 v[18:19], v[18:19], v[38:39]
	v_pk_fma_f32 v[38:39], v[42:43], v[38:39], v[44:45]
	v_pk_fma_f32 v[30:31], v[32:33], v[40:41], v[30:31]
	v_pk_fma_f32 v[54:55], v[84:85], v[22:23], v[18:19] op_sel_hi:[0,1,1]
	v_add_f32_e32 v18, v30, v31
	v_add_f32_e32 v94, v38, v39
	v_pk_mul_f32 v[20:21], v[20:21], v[40:41]
	v_add_f32_dpp v0, v18, v18 quad_perm:[1,0,3,2] row_mask:0xf bank_mask:0xf bound_ctrl:1
	v_pk_fma_f32 v[56:57], v[84:85], v[24:25], v[20:21] op_sel_hi:[0,1,1]
	ds_read_b128 v[18:21], v90 offset:3328
	v_add_f32_dpp v0, v0, v0 quad_perm:[2,3,0,1] row_mask:0xf bank_mask:0xf bound_ctrl:1
	ds_read_b128 v[22:25], v89 offset:7424
	ds_read_b128 v[30:33], v90 offset:7424
	v_add_f32_dpp v0, v0, v0 row_half_mirror row_mask:0xf bank_mask:0xf bound_ctrl:1
	ds_read_b128 v[38:41], v90 offset:11520
	ds_read_b128 v[42:45], v89 offset:19712
	v_add_f32_dpp v0, v0, v0 row_ror:8 row_mask:0xf bank_mask:0xf bound_ctrl:1
	s_waitcnt lgkmcnt(11)
	v_pk_fma_f32 v[34:35], v[34:35], v[0:1], v[54:55] op_sel_hi:[1,0,1] neg_lo:[1,0,0] neg_hi:[1,0,0]
	v_pk_fma_f32 v[36:37], v[36:37], v[0:1], v[56:57] op_sel_hi:[1,0,1] neg_lo:[1,0,0] neg_hi:[1,0,0]
	s_waitcnt lgkmcnt(7)
	v_pk_mul_f32 v[14:15], v[14:15], v[34:35]
	v_pk_mul_f32 v[48:49], v[48:49], v[36:37]
	v_pk_mul_f32 v[6:7], v[6:7], v[34:35]
	v_pk_fma_f32 v[34:35], v[46:47], v[34:35], v[48:49]
	v_pk_fma_f32 v[14:15], v[16:17], v[36:37], v[14:15]
	v_pk_fma_f32 v[54:55], v[2:3], v[10:11], v[6:7] op_sel_hi:[0,1,1]
	v_add_f32_e32 v95, v34, v35
	v_add_f32_e32 v6, v14, v15
	ds_write_b128 v91, v[92:95] offset:51200
	v_pk_mul_f32 v[8:9], v[8:9], v[36:37]
	v_add_f32_dpp v0, v6, v6 quad_perm:[1,0,3,2] row_mask:0xf bank_mask:0xf bound_ctrl:1
	v_pk_fma_f32 v[56:57], v[2:3], v[12:13], v[8:9] op_sel_hi:[0,1,1]
	ds_read_b128 v[6:9], v90 offset:3584
	v_add_f32_dpp v0, v0, v0 quad_perm:[2,3,0,1] row_mask:0xf bank_mask:0xf bound_ctrl:1
	ds_read_b128 v[10:13], v89 offset:7680
	ds_read_b128 v[14:17], v90 offset:7680
	v_add_f32_dpp v0, v0, v0 row_half_mirror row_mask:0xf bank_mask:0xf bound_ctrl:1
	ds_read_b128 v[34:37], v90 offset:11776
	ds_read_b128 v[46:49], v89 offset:19968
	v_add_f32_dpp v0, v0, v0 row_ror:8 row_mask:0xf bank_mask:0xf bound_ctrl:1
	s_waitcnt lgkmcnt(12)
	v_pk_fma_f32 v[26:27], v[26:27], v[0:1], v[54:55] op_sel_hi:[1,0,1] neg_lo:[1,0,0] neg_hi:[1,0,0]
	v_pk_fma_f32 v[28:29], v[28:29], v[0:1], v[56:57] op_sel_hi:[1,0,1] neg_lo:[1,0,0] neg_hi:[1,0,0]
	s_waitcnt lgkmcnt(8)
	v_pk_mul_f32 v[30:31], v[30:31], v[26:27]
	v_pk_mul_f32 v[52:53], v[52:53], v[28:29]
	v_pk_mul_f32 v[18:19], v[18:19], v[26:27]
	v_pk_mul_f32 v[20:21], v[20:21], v[28:29]
	v_pk_fma_f32 v[26:27], v[50:51], v[26:27], v[52:53]
	v_pk_fma_f32 v[28:29], v[32:33], v[28:29], v[30:31]
	v_pk_fma_f32 v[54:55], v[2:3], v[22:23], v[18:19] op_sel:[1,0,0]
	v_add_f32_e32 v18, v28, v29
	v_add_f32_e32 v96, v26, v27
	v_pk_fma_f32 v[2:3], v[2:3], v[24:25], v[20:21] op_sel:[1,0,0]
	v_add_f32_dpp v0, v18, v18 quad_perm:[1,0,3,2] row_mask:0xf bank_mask:0xf bound_ctrl:1
	ds_read_b128 v[18:21], v90 offset:3840
	ds_read_b128 v[22:25], v89 offset:7936
	v_add_f32_dpp v0, v0, v0 quad_perm:[2,3,0,1] row_mask:0xf bank_mask:0xf bound_ctrl:1
	ds_read_b128 v[26:29], v90 offset:7936
	ds_read_b128 v[30:33], v90 offset:12032
	v_add_f32_dpp v0, v0, v0 row_half_mirror row_mask:0xf bank_mask:0xf bound_ctrl:1
	ds_read_b128 v[50:53], v89 offset:20224
	s_waitcnt lgkmcnt(12)
	v_add_f32_dpp v0, v0, v0 row_ror:8 row_mask:0xf bank_mask:0xf bound_ctrl:1
	v_pk_fma_f32 v[38:39], v[38:39], v[0:1], v[54:55] op_sel_hi:[1,0,1] neg_lo:[1,0,0] neg_hi:[1,0,0]
	v_pk_fma_f32 v[2:3], v[40:41], v[0:1], v[2:3] op_sel_hi:[1,0,1] neg_lo:[1,0,0] neg_hi:[1,0,0]
	s_waitcnt lgkmcnt(7)
	v_pk_mul_f32 v[14:15], v[14:15], v[38:39]
	v_pk_mul_f32 v[40:41], v[44:45], v[2:3]
	v_pk_mul_f32 v[8:9], v[8:9], v[2:3]
	v_pk_fma_f32 v[2:3], v[16:17], v[2:3], v[14:15]
	v_pk_mul_f32 v[6:7], v[6:7], v[38:39]
	v_add_f32_e32 v0, v2, v3
	v_pk_fma_f32 v[6:7], v[4:5], v[10:11], v[6:7] op_sel_hi:[0,1,1]
	v_pk_fma_f32 v[4:5], v[4:5], v[12:13], v[8:9] op_sel_hi:[0,1,1]
	v_add_f32_dpp v0, v0, v0 quad_perm:[1,0,3,2] row_mask:0xf bank_mask:0xf bound_ctrl:1
	v_pk_fma_f32 v[38:39], v[42:43], v[38:39], v[40:41]
	ds_read_b128 v[108:111], v88 offset:4096
	v_add_f32_dpp v0, v0, v0 quad_perm:[2,3,0,1] row_mask:0xf bank_mask:0xf bound_ctrl:1
	v_add_f32_e32 v97, v38, v39
	ds_read_b128 v[100:103], v88
	v_add_f32_dpp v0, v0, v0 row_half_mirror row_mask:0xf bank_mask:0xf bound_ctrl:1
	ds_read_b128 v[120:123], v88 offset:8192
	ds_read_b128 v[112:115], v88 offset:4352
	v_add_f32_dpp v0, v0, v0 row_ror:8 row_mask:0xf bank_mask:0xf bound_ctrl:1
	s_waitcnt lgkmcnt(10)
	v_pk_fma_f32 v[2:3], v[34:35], v[0:1], v[6:7] op_sel_hi:[1,0,1] neg_lo:[1,0,0] neg_hi:[1,0,0]
	v_pk_fma_f32 v[4:5], v[36:37], v[0:1], v[4:5] op_sel_hi:[1,0,1] neg_lo:[1,0,0] neg_hi:[1,0,0]
	s_waitcnt lgkmcnt(6)
	v_pk_mul_f32 v[8:9], v[26:27], v[2:3]
	v_pk_mul_f32 v[6:7], v[48:49], v[4:5]
	v_pk_mul_f32 v[10:11], v[18:19], v[2:3]
	v_pk_mul_f32 v[12:13], v[20:21], v[4:5]
	v_pk_fma_f32 v[2:3], v[46:47], v[2:3], v[6:7]
	v_pk_fma_f32 v[4:5], v[28:29], v[4:5], v[8:9]
	v_add_f32_e32 v98, v2, v3
	v_add_f32_e32 v2, v4, v5
	v_pk_fma_f32 v[8:9], v[86:87], v[24:25], v[12:13] op_sel_hi:[0,1,1]
	s_nop 0
	v_add_f32_dpp v0, v2, v2 quad_perm:[1,0,3,2] row_mask:0xf bank_mask:0xf bound_ctrl:1
	v_pk_fma_f32 v[6:7], v[86:87], v[22:23], v[10:11] op_sel_hi:[0,1,1]
	ds_read_b128 v[104:107], v88 offset:256
	v_add_f32_dpp v0, v0, v0 quad_perm:[2,3,0,1] row_mask:0xf bank_mask:0xf bound_ctrl:1
	ds_read_b128 v[128:131], v88 offset:8448
	ds_read_b128 v[124:127], v88 offset:4608
	v_add_f32_dpp v0, v0, v0 row_half_mirror row_mask:0xf bank_mask:0xf bound_ctrl:1
	ds_read_b128 v[116:119], v88 offset:512
	ds_read_b128 v[132:135], v88 offset:8704
	v_add_f32_dpp v0, v0, v0 row_ror:8 row_mask:0xf bank_mask:0xf bound_ctrl:1
	s_waitcnt lgkmcnt(10)
	v_pk_fma_f32 v[76:77], v[32:33], v[0:1], v[8:9] op_sel_hi:[1,0,1] neg_lo:[1,0,0] neg_hi:[1,0,0]
	v_pk_fma_f32 v[74:75], v[30:31], v[0:1], v[6:7] op_sel_hi:[1,0,1] neg_lo:[1,0,0] neg_hi:[1,0,0]
	s_waitcnt lgkmcnt(9)
	v_pk_mul_f32 v[2:3], v[52:53], v[76:77]
	s_nop 0
	v_pk_fma_f32 v[2:3], v[50:51], v[74:75], v[2:3]
	s_nop 0
	v_add_f32_e32 v99, v2, v3
	ds_write_b128 v91, v[96:99] offset:55296
	s_and_b32 s2, s26, 1
	s_mul_i32 s3, s2, 0x5400
	v_lshlrev_b32_e32 v91, 2, v87
	v_lshl_add_u32 v91, s2, 14, v91
	s_add_i32 s2, s3, 0
	v_add_u32_e32 v0, s2, v85
	v_add_u32_e32 v89, s2, v83
	v_add_u32_e32 v90, s96, v83
	s_add_i32 s96, s96, 0x3000
	s_cmp_eq_u32 s96, 0x1e800
	s_cselect_b32 s96, 0x20200, s96
	s_cmp_eq_u32 s96, 0x23200
	s_cselect_b32 s96, 0x12800, s96
	v_add_u32_e32 v88, s96, v83
	s_cmpk_eq_i32 s26, 0x110
	s_waitcnt lgkmcnt(0)
	s_cbranch_scc0 .LBB0_1050
	s_barrier
	s_setprio 0
